# HGRN combine item rewritten by hand: scalar bases, all 69 loads of an item in flight behind counted waits (the compiler's loop waited vmcnt(0) after each decay load)
# speedup vs baseline: 1.0187x; 1.0070x over previous
; DEV float bflo(unsigned w) { return __uint_as_float(w << 16); }
; DEV float bfhi(unsigned w) { return __uint_as_float(w & 0xffff0000u); }
; DEV void hg_combine_item(const Params& p, int item, int tid) {
;   const int e = (item * 512 + tid) * 2;
;   const int sc = e >> 12, el = e & 4095, d = el & 63;
;   u16* base = p.Sloc + (long)sc * NSEG * 4096 + el;
;   const float* db = p.Dseg + (long)sc * NSEG * 64 + d;
;   unsigned vals[NSEG - 1];
;   float2 dd[NSEG - 1];
; #pragma unroll
;   for (int k = 0; k < NSEG - 1; ++k) { vals[k] = *(const unsigned*)(base + (long)k * 4096); dd[k] = *(const float2*)(db + k * 64); }
;   float s0 = bflo(vals[0]), s1 = bfhi(vals[0]);
; #pragma unroll
;   for (int k = 1; k < NSEG - 1; ++k) {
;     s0 = fmaf(dd[k].x, s0, bflo(vals[k]));
;     s1 = fmaf(dd[k].y, s1, bfhi(vals[k]));
;     *(unsigned*)(base + (long)k * 4096) = pack2(s0, s1);
;   }
; }
.LBB0_979:
	s_add_i32 s7, s7, s6
	s_lshr_b32 s15, s8, 12
	s_and_b32 s16, s8, 0xfff
	s_add_i32 s8, s8, s9
	s_mul_i32 s18, s15, 0x48000
	s_lshl_b32 s16, s16, 1
	s_add_u32 s18, s18, s16
	s_add_u32 s10, s22, s18
	s_addc_u32 s11, s23, 0
	s_mul_i32 s18, s15, 0x2400
	s_add_u32 s12, s20, s18
	s_addc_u32 s13, s21, 0
	v_lshlrev_b32_e32 v0, 2, v197
	v_lshlrev_b32_e32 v1, 3, v197
	v_and_b32_e32 v1, 0xf8, v1
	global_load_dword v2, v0, s[10:11]
	s_add_u32 s10, s10, 0x2000
	s_addc_u32 s11, s11, 0
	global_load_dword v3, v0, s[10:11]
	s_add_u32 s10, s10, 0x2000
	s_addc_u32 s11, s11, 0
	global_load_dwordx2 v[38:39], v1, s[12:13] offset:256
	global_load_dword v4, v0, s[10:11]
	s_add_u32 s10, s10, 0x2000
	s_addc_u32 s11, s11, 0
	global_load_dwordx2 v[40:41], v1, s[12:13] offset:512
	global_load_dword v5, v0, s[10:11]
	s_add_u32 s10, s10, 0x2000
	s_addc_u32 s11, s11, 0
	global_load_dwordx2 v[42:43], v1, s[12:13] offset:768
	global_load_dword v6, v0, s[10:11]
	s_add_u32 s10, s10, 0x2000
	s_addc_u32 s11, s11, 0
	global_load_dwordx2 v[44:45], v1, s[12:13] offset:1024
	global_load_dword v7, v0, s[10:11]
	s_add_u32 s10, s10, 0x2000
	s_addc_u32 s11, s11, 0
	global_load_dwordx2 v[46:47], v1, s[12:13] offset:1280
	global_load_dword v8, v0, s[10:11]
	s_add_u32 s10, s10, 0x2000
	s_addc_u32 s11, s11, 0
	global_load_dwordx2 v[48:49], v1, s[12:13] offset:1536
	global_load_dword v9, v0, s[10:11]
	s_add_u32 s10, s10, 0x2000
	s_addc_u32 s11, s11, 0
	global_load_dwordx2 v[50:51], v1, s[12:13] offset:1792
	global_load_dword v10, v0, s[10:11]
	s_add_u32 s10, s10, 0x2000
	s_addc_u32 s11, s11, 0
	global_load_dwordx2 v[52:53], v1, s[12:13] offset:2048
	global_load_dword v11, v0, s[10:11]
	s_add_u32 s10, s10, 0x2000
	s_addc_u32 s11, s11, 0
	global_load_dwordx2 v[54:55], v1, s[12:13] offset:2304
	global_load_dword v12, v0, s[10:11]
	s_add_u32 s10, s10, 0x2000
	s_addc_u32 s11, s11, 0
	global_load_dwordx2 v[56:57], v1, s[12:13] offset:2560
	global_load_dword v13, v0, s[10:11]
	s_add_u32 s10, s10, 0x2000
	s_addc_u32 s11, s11, 0
	global_load_dwordx2 v[58:59], v1, s[12:13] offset:2816
	global_load_dword v14, v0, s[10:11]
	s_add_u32 s10, s10, 0x2000
	s_addc_u32 s11, s11, 0
	global_load_dwordx2 v[60:61], v1, s[12:13] offset:3072
	global_load_dword v15, v0, s[10:11]
	s_add_u32 s10, s10, 0x2000
	s_addc_u32 s11, s11, 0
	global_load_dwordx2 v[62:63], v1, s[12:13] offset:3328
	global_load_dword v16, v0, s[10:11]
	s_add_u32 s10, s10, 0x2000
	s_addc_u32 s11, s11, 0
	global_load_dwordx2 v[64:65], v1, s[12:13] offset:3584
	global_load_dword v17, v0, s[10:11]
	s_add_u32 s10, s10, 0x2000
	s_addc_u32 s11, s11, 0
	global_load_dwordx2 v[66:67], v1, s[12:13] offset:3840
	global_load_dword v18, v0, s[10:11]
	s_add_u32 s10, s10, 0x2000
	s_addc_u32 s11, s11, 0
	s_add_u32 s12, s12, 0x1000
	s_addc_u32 s13, s13, 0
	global_load_dwordx2 v[68:69], v1, s[12:13]
	global_load_dword v19, v0, s[10:11]
	s_add_u32 s10, s10, 0x2000
	s_addc_u32 s11, s11, 0
	global_load_dwordx2 v[70:71], v1, s[12:13] offset:256
	global_load_dword v20, v0, s[10:11]
	s_add_u32 s10, s10, 0x2000
	s_addc_u32 s11, s11, 0
	global_load_dwordx2 v[72:73], v1, s[12:13] offset:512
	global_load_dword v21, v0, s[10:11]
	s_add_u32 s10, s10, 0x2000
	s_addc_u32 s11, s11, 0
	global_load_dwordx2 v[74:75], v1, s[12:13] offset:768
	global_load_dword v22, v0, s[10:11]
	s_add_u32 s10, s10, 0x2000
	s_addc_u32 s11, s11, 0
	global_load_dwordx2 v[76:77], v1, s[12:13] offset:1024
	global_load_dword v23, v0, s[10:11]
	s_add_u32 s10, s10, 0x2000
	s_addc_u32 s11, s11, 0
	global_load_dwordx2 v[78:79], v1, s[12:13] offset:1280
	global_load_dword v24, v0, s[10:11]
	s_add_u32 s10, s10, 0x2000
	s_addc_u32 s11, s11, 0
	global_load_dwordx2 v[80:81], v1, s[12:13] offset:1536
	global_load_dword v25, v0, s[10:11]
	s_add_u32 s10, s10, 0x2000
	s_addc_u32 s11, s11, 0
	global_load_dwordx2 v[82:83], v1, s[12:13] offset:1792
	global_load_dword v26, v0, s[10:11]
	s_add_u32 s10, s10, 0x2000
	s_addc_u32 s11, s11, 0
	global_load_dwordx2 v[84:85], v1, s[12:13] offset:2048
	global_load_dword v27, v0, s[10:11]
	s_add_u32 s10, s10, 0x2000
	s_addc_u32 s11, s11, 0
	global_load_dwordx2 v[86:87], v1, s[12:13] offset:2304
	global_load_dword v28, v0, s[10:11]
	s_add_u32 s10, s10, 0x2000
	s_addc_u32 s11, s11, 0
	s_sub_u32 s18, s10, 0x34000
	s_subb_u32 s19, s11, 0
	s_waitcnt vmcnt(51)
	v_lshlrev_b32_e32 v106, 16, v2
	v_and_b32_e32 v107, 0xffff0000, v2
	global_load_dwordx2 v[88:89], v1, s[12:13] offset:2560
	global_load_dword v29, v0, s[10:11]
	s_add_u32 s10, s10, 0x2000
	s_addc_u32 s11, s11, 0
	s_waitcnt vmcnt(51)
	v_lshlrev_b32_e32 v108, 16, v3
	v_and_b32_e32 v109, 0xffff0000, v3
	v_pk_fma_f32 v[106:107], v[38:39], v[106:107], v[108:109]
	v_cvt_pk_bf16_f32 v110, v106, v107
	global_store_dword v0, v110, s[18:19]
	s_add_u32 s18, s18, 0x2000
	s_addc_u32 s19, s19, 0
	global_load_dwordx2 v[90:91], v1, s[12:13] offset:2816
	global_load_dword v30, v0, s[10:11]
	s_add_u32 s10, s10, 0x2000
	s_addc_u32 s11, s11, 0
	s_waitcnt vmcnt(52)
	v_lshlrev_b32_e32 v108, 16, v4
	v_and_b32_e32 v109, 0xffff0000, v4
	v_pk_fma_f32 v[106:107], v[40:41], v[106:107], v[108:109]
	v_cvt_pk_bf16_f32 v110, v106, v107
	global_store_dword v0, v110, s[18:19]
	s_add_u32 s18, s18, 0x2000
	s_addc_u32 s19, s19, 0
	global_load_dwordx2 v[92:93], v1, s[12:13] offset:3072
	global_load_dword v31, v0, s[10:11]
	s_add_u32 s10, s10, 0x2000
	s_addc_u32 s11, s11, 0
	s_waitcnt vmcnt(53)
	v_lshlrev_b32_e32 v108, 16, v5
	v_and_b32_e32 v109, 0xffff0000, v5
	v_pk_fma_f32 v[106:107], v[42:43], v[106:107], v[108:109]
	v_cvt_pk_bf16_f32 v110, v106, v107
	global_store_dword v0, v110, s[18:19]
	s_add_u32 s18, s18, 0x2000
	s_addc_u32 s19, s19, 0
	global_load_dwordx2 v[94:95], v1, s[12:13] offset:3328
	global_load_dword v32, v0, s[10:11]
	s_add_u32 s10, s10, 0x2000
	s_addc_u32 s11, s11, 0
	s_waitcnt vmcnt(54)
; DEV float bflo(unsigned w) { return __uint_as_float(w << 16); }
; DEV float bfhi(unsigned w) { return __uint_as_float(w & 0xffff0000u); }
; DEV void hg_combine_item(const Params& p, int item, int tid) {
;   const int e = (item * 512 + tid) * 2;
;   const int sc = e >> 12, el = e & 4095, d = el & 63;
;   u16* base = p.Sloc + (long)sc * NSEG * 4096 + el;
;   const float* db = p.Dseg + (long)sc * NSEG * 64 + d;
;   unsigned vals[NSEG - 1];
;   float2 dd[NSEG - 1];
; #pragma unroll
;   for (int k = 0; k < NSEG - 1; ++k) { vals[k] = *(const unsigned*)(base + (long)k * 4096); dd[k] = *(const float2*)(db + k * 64); }
;   float s0 = bflo(vals[0]), s1 = bfhi(vals[0]);
; #pragma unroll
;   for (int k = 1; k < NSEG - 1; ++k) {
;     s0 = fmaf(dd[k].x, s0, bflo(vals[k]));
;     s1 = fmaf(dd[k].y, s1, bfhi(vals[k]));
;     *(unsigned*)(base + (long)k * 4096) = pack2(s0, s1);
;   }
; }
	v_lshlrev_b32_e32 v108, 16, v6
	v_and_b32_e32 v109, 0xffff0000, v6
	v_pk_fma_f32 v[106:107], v[44:45], v[106:107], v[108:109]
	v_cvt_pk_bf16_f32 v110, v106, v107
	global_store_dword v0, v110, s[18:19]
	s_add_u32 s18, s18, 0x2000
	s_addc_u32 s19, s19, 0
	global_load_dwordx2 v[96:97], v1, s[12:13] offset:3584
	global_load_dword v33, v0, s[10:11]
	s_add_u32 s10, s10, 0x2000
	s_addc_u32 s11, s11, 0
	s_waitcnt vmcnt(55)
	v_lshlrev_b32_e32 v108, 16, v7
	v_and_b32_e32 v109, 0xffff0000, v7
	v_pk_fma_f32 v[106:107], v[46:47], v[106:107], v[108:109]
	v_cvt_pk_bf16_f32 v110, v106, v107
	global_store_dword v0, v110, s[18:19]
	s_add_u32 s18, s18, 0x2000
	s_addc_u32 s19, s19, 0
	global_load_dwordx2 v[98:99], v1, s[12:13] offset:3840
	global_load_dword v34, v0, s[10:11]
	s_add_u32 s10, s10, 0x2000
	s_addc_u32 s11, s11, 0
	s_waitcnt vmcnt(56)
	v_lshlrev_b32_e32 v108, 16, v8
	v_and_b32_e32 v109, 0xffff0000, v8
	v_pk_fma_f32 v[106:107], v[48:49], v[106:107], v[108:109]
	v_cvt_pk_bf16_f32 v110, v106, v107
	global_store_dword v0, v110, s[18:19]
	s_add_u32 s18, s18, 0x2000
	s_addc_u32 s19, s19, 0
	s_add_u32 s12, s12, 0x1000
	s_addc_u32 s13, s13, 0
	global_load_dwordx2 v[100:101], v1, s[12:13]
	global_load_dword v35, v0, s[10:11]
	s_add_u32 s10, s10, 0x2000
	s_addc_u32 s11, s11, 0
	s_waitcnt vmcnt(57)
	v_lshlrev_b32_e32 v108, 16, v9
	v_and_b32_e32 v109, 0xffff0000, v9
	v_pk_fma_f32 v[106:107], v[50:51], v[106:107], v[108:109]
	v_cvt_pk_bf16_f32 v110, v106, v107
	global_store_dword v0, v110, s[18:19]
	s_add_u32 s18, s18, 0x2000
	s_addc_u32 s19, s19, 0
	global_load_dwordx2 v[102:103], v1, s[12:13] offset:256
	global_load_dword v36, v0, s[10:11]
	s_add_u32 s10, s10, 0x2000
	s_addc_u32 s11, s11, 0
	s_waitcnt vmcnt(58)
	v_lshlrev_b32_e32 v108, 16, v10
	v_and_b32_e32 v109, 0xffff0000, v10
	v_pk_fma_f32 v[106:107], v[52:53], v[106:107], v[108:109]
	v_cvt_pk_bf16_f32 v110, v106, v107
	global_store_dword v0, v110, s[18:19]
	s_add_u32 s18, s18, 0x2000
	s_addc_u32 s19, s19, 0
	global_load_dwordx2 v[104:105], v1, s[12:13] offset:512
	s_waitcnt vmcnt(58)
	v_lshlrev_b32_e32 v108, 16, v11
	v_and_b32_e32 v109, 0xffff0000, v11
	v_pk_fma_f32 v[106:107], v[54:55], v[106:107], v[108:109]
	v_cvt_pk_bf16_f32 v110, v106, v107
	global_store_dword v0, v110, s[18:19]
	s_add_u32 s18, s18, 0x2000
	s_addc_u32 s19, s19, 0
	s_waitcnt vmcnt(57)
	v_lshlrev_b32_e32 v108, 16, v12
	v_and_b32_e32 v109, 0xffff0000, v12
	v_pk_fma_f32 v[106:107], v[56:57], v[106:107], v[108:109]
	v_cvt_pk_bf16_f32 v110, v106, v107
	global_store_dword v0, v110, s[18:19]
	s_add_u32 s18, s18, 0x2000
	s_addc_u32 s19, s19, 0
	s_waitcnt vmcnt(56)
	v_lshlrev_b32_e32 v108, 16, v13
	v_and_b32_e32 v109, 0xffff0000, v13
	v_pk_fma_f32 v[106:107], v[58:59], v[106:107], v[108:109]
	v_cvt_pk_bf16_f32 v110, v106, v107
	global_store_dword v0, v110, s[18:19]
	s_add_u32 s18, s18, 0x2000
	s_addc_u32 s19, s19, 0
	s_waitcnt vmcnt(55)
	v_lshlrev_b32_e32 v108, 16, v14
	v_and_b32_e32 v109, 0xffff0000, v14
	v_pk_fma_f32 v[106:107], v[60:61], v[106:107], v[108:109]
	v_cvt_pk_bf16_f32 v110, v106, v107
	global_store_dword v0, v110, s[18:19]
	s_add_u32 s18, s18, 0x2000
	s_addc_u32 s19, s19, 0
	s_waitcnt vmcnt(54)
	v_lshlrev_b32_e32 v108, 16, v15
	v_and_b32_e32 v109, 0xffff0000, v15
	v_pk_fma_f32 v[106:107], v[62:63], v[106:107], v[108:109]
	v_cvt_pk_bf16_f32 v110, v106, v107
	global_store_dword v0, v110, s[18:19]
	s_add_u32 s18, s18, 0x2000
	s_addc_u32 s19, s19, 0
	s_waitcnt vmcnt(53)
	v_lshlrev_b32_e32 v108, 16, v16
	v_and_b32_e32 v109, 0xffff0000, v16
	v_pk_fma_f32 v[106:107], v[64:65], v[106:107], v[108:109]
	v_cvt_pk_bf16_f32 v110, v106, v107
	global_store_dword v0, v110, s[18:19]
	s_add_u32 s18, s18, 0x2000
	s_addc_u32 s19, s19, 0
	s_waitcnt vmcnt(52)
	v_lshlrev_b32_e32 v108, 16, v17
	v_and_b32_e32 v109, 0xffff0000, v17
	v_pk_fma_f32 v[106:107], v[66:67], v[106:107], v[108:109]
	v_cvt_pk_bf16_f32 v110, v106, v107
	global_store_dword v0, v110, s[18:19]
	s_add_u32 s18, s18, 0x2000
	s_addc_u32 s19, s19, 0
	s_waitcnt vmcnt(51)
	v_lshlrev_b32_e32 v108, 16, v18
	v_and_b32_e32 v109, 0xffff0000, v18
	v_pk_fma_f32 v[106:107], v[68:69], v[106:107], v[108:109]
	v_cvt_pk_bf16_f32 v110, v106, v107
	global_store_dword v0, v110, s[18:19]
	s_add_u32 s18, s18, 0x2000
	s_addc_u32 s19, s19, 0
	s_waitcnt vmcnt(50)
	v_lshlrev_b32_e32 v108, 16, v19
	v_and_b32_e32 v109, 0xffff0000, v19
	v_pk_fma_f32 v[106:107], v[70:71], v[106:107], v[108:109]
	v_cvt_pk_bf16_f32 v110, v106, v107
	global_store_dword v0, v110, s[18:19]
	s_add_u32 s18, s18, 0x2000
	s_addc_u32 s19, s19, 0
	s_waitcnt vmcnt(49)
; DEV float bflo(unsigned w) { return __uint_as_float(w << 16); }
; DEV float bfhi(unsigned w) { return __uint_as_float(w & 0xffff0000u); }
; DEV void hg_combine_item(const Params& p, int item, int tid) {
;   const int e = (item * 512 + tid) * 2;
;   const int sc = e >> 12, el = e & 4095, d = el & 63;
;   u16* base = p.Sloc + (long)sc * NSEG * 4096 + el;
;   const float* db = p.Dseg + (long)sc * NSEG * 64 + d;
;   unsigned vals[NSEG - 1];
;   float2 dd[NSEG - 1];
; #pragma unroll
;   for (int k = 0; k < NSEG - 1; ++k) { vals[k] = *(const unsigned*)(base + (long)k * 4096); dd[k] = *(const float2*)(db + k * 64); }
;   float s0 = bflo(vals[0]), s1 = bfhi(vals[0]);
; #pragma unroll
;   for (int k = 1; k < NSEG - 1; ++k) {
;     s0 = fmaf(dd[k].x, s0, bflo(vals[k]));
;     s1 = fmaf(dd[k].y, s1, bfhi(vals[k]));
;     *(unsigned*)(base + (long)k * 4096) = pack2(s0, s1);
;   }
; }
	v_lshlrev_b32_e32 v108, 16, v20
	v_and_b32_e32 v109, 0xffff0000, v20
	v_pk_fma_f32 v[106:107], v[72:73], v[106:107], v[108:109]
	v_cvt_pk_bf16_f32 v110, v106, v107
	global_store_dword v0, v110, s[18:19]
	s_add_u32 s18, s18, 0x2000
	s_addc_u32 s19, s19, 0
	s_waitcnt vmcnt(48)
	v_lshlrev_b32_e32 v108, 16, v21
	v_and_b32_e32 v109, 0xffff0000, v21
	v_pk_fma_f32 v[106:107], v[74:75], v[106:107], v[108:109]
	v_cvt_pk_bf16_f32 v110, v106, v107
	global_store_dword v0, v110, s[18:19]
	s_add_u32 s18, s18, 0x2000
	s_addc_u32 s19, s19, 0
	s_waitcnt vmcnt(47)
	v_lshlrev_b32_e32 v108, 16, v22
	v_and_b32_e32 v109, 0xffff0000, v22
	v_pk_fma_f32 v[106:107], v[76:77], v[106:107], v[108:109]
	v_cvt_pk_bf16_f32 v110, v106, v107
	global_store_dword v0, v110, s[18:19]
	s_add_u32 s18, s18, 0x2000
	s_addc_u32 s19, s19, 0
	s_waitcnt vmcnt(46)
	v_lshlrev_b32_e32 v108, 16, v23
	v_and_b32_e32 v109, 0xffff0000, v23
	v_pk_fma_f32 v[106:107], v[78:79], v[106:107], v[108:109]
	v_cvt_pk_bf16_f32 v110, v106, v107
	global_store_dword v0, v110, s[18:19]
	s_add_u32 s18, s18, 0x2000
	s_addc_u32 s19, s19, 0
	s_waitcnt vmcnt(45)
	v_lshlrev_b32_e32 v108, 16, v24
	v_and_b32_e32 v109, 0xffff0000, v24
	v_pk_fma_f32 v[106:107], v[80:81], v[106:107], v[108:109]
	v_cvt_pk_bf16_f32 v110, v106, v107
	global_store_dword v0, v110, s[18:19]
	s_add_u32 s18, s18, 0x2000
	s_addc_u32 s19, s19, 0
	s_waitcnt vmcnt(44)
	v_lshlrev_b32_e32 v108, 16, v25
	v_and_b32_e32 v109, 0xffff0000, v25
	v_pk_fma_f32 v[106:107], v[82:83], v[106:107], v[108:109]
	v_cvt_pk_bf16_f32 v110, v106, v107
	global_store_dword v0, v110, s[18:19]
	s_add_u32 s18, s18, 0x2000
	s_addc_u32 s19, s19, 0
	s_waitcnt vmcnt(43)
	v_lshlrev_b32_e32 v108, 16, v26
	v_and_b32_e32 v109, 0xffff0000, v26
	v_pk_fma_f32 v[106:107], v[84:85], v[106:107], v[108:109]
	v_cvt_pk_bf16_f32 v110, v106, v107
	global_store_dword v0, v110, s[18:19]
	s_add_u32 s18, s18, 0x2000
	s_addc_u32 s19, s19, 0
	s_waitcnt vmcnt(42)
	v_lshlrev_b32_e32 v108, 16, v27
	v_and_b32_e32 v109, 0xffff0000, v27
	v_pk_fma_f32 v[106:107], v[86:87], v[106:107], v[108:109]
	v_cvt_pk_bf16_f32 v110, v106, v107
	global_store_dword v0, v110, s[18:19]
	s_add_u32 s18, s18, 0x2000
	s_addc_u32 s19, s19, 0
	s_waitcnt vmcnt(41)
	v_lshlrev_b32_e32 v108, 16, v28
	v_and_b32_e32 v109, 0xffff0000, v28
	v_pk_fma_f32 v[106:107], v[88:89], v[106:107], v[108:109]
	v_cvt_pk_bf16_f32 v110, v106, v107
	global_store_dword v0, v110, s[18:19]
	s_add_u32 s18, s18, 0x2000
	s_addc_u32 s19, s19, 0
	s_waitcnt vmcnt(39)
	v_lshlrev_b32_e32 v108, 16, v29
	v_and_b32_e32 v109, 0xffff0000, v29
	v_pk_fma_f32 v[106:107], v[90:91], v[106:107], v[108:109]
	v_cvt_pk_bf16_f32 v110, v106, v107
	global_store_dword v0, v110, s[18:19]
	s_add_u32 s18, s18, 0x2000
	s_addc_u32 s19, s19, 0
	s_waitcnt vmcnt(37)
	v_lshlrev_b32_e32 v108, 16, v30
	v_and_b32_e32 v109, 0xffff0000, v30
	v_pk_fma_f32 v[106:107], v[92:93], v[106:107], v[108:109]
	v_cvt_pk_bf16_f32 v110, v106, v107
	global_store_dword v0, v110, s[18:19]
	s_add_u32 s18, s18, 0x2000
	s_addc_u32 s19, s19, 0
	s_waitcnt vmcnt(35)
	v_lshlrev_b32_e32 v108, 16, v31
	v_and_b32_e32 v109, 0xffff0000, v31
	v_pk_fma_f32 v[106:107], v[94:95], v[106:107], v[108:109]
	v_cvt_pk_bf16_f32 v110, v106, v107
	global_store_dword v0, v110, s[18:19]
	s_add_u32 s18, s18, 0x2000
	s_addc_u32 s19, s19, 0
	s_waitcnt vmcnt(33)
	v_lshlrev_b32_e32 v108, 16, v32
	v_and_b32_e32 v109, 0xffff0000, v32
	v_pk_fma_f32 v[106:107], v[96:97], v[106:107], v[108:109]
	v_cvt_pk_bf16_f32 v110, v106, v107
	global_store_dword v0, v110, s[18:19]
	s_add_u32 s18, s18, 0x2000
	s_addc_u32 s19, s19, 0
	s_waitcnt vmcnt(31)
	v_lshlrev_b32_e32 v108, 16, v33
	v_and_b32_e32 v109, 0xffff0000, v33
	v_pk_fma_f32 v[106:107], v[98:99], v[106:107], v[108:109]
	v_cvt_pk_bf16_f32 v110, v106, v107
	global_store_dword v0, v110, s[18:19]
	s_add_u32 s18, s18, 0x2000
	s_addc_u32 s19, s19, 0
	s_waitcnt vmcnt(29)
	v_lshlrev_b32_e32 v108, 16, v34
	v_and_b32_e32 v109, 0xffff0000, v34
	v_pk_fma_f32 v[106:107], v[100:101], v[106:107], v[108:109]
	v_cvt_pk_bf16_f32 v110, v106, v107
	global_store_dword v0, v110, s[18:19]
	s_add_u32 s18, s18, 0x2000
	s_addc_u32 s19, s19, 0
	s_waitcnt vmcnt(27)
	v_lshlrev_b32_e32 v108, 16, v35
	v_and_b32_e32 v109, 0xffff0000, v35
	v_pk_fma_f32 v[106:107], v[102:103], v[106:107], v[108:109]
	v_cvt_pk_bf16_f32 v110, v106, v107
	global_store_dword v0, v110, s[18:19]
	s_add_u32 s18, s18, 0x2000
	s_addc_u32 s19, s19, 0
	s_waitcnt vmcnt(25)
	v_lshlrev_b32_e32 v108, 16, v36
	v_and_b32_e32 v109, 0xffff0000, v36
	v_pk_fma_f32 v[106:107], v[104:105], v[106:107], v[108:109]
	v_cvt_pk_bf16_f32 v110, v106, v107
	global_store_dword v0, v110, s[18:19]
	s_add_u32 s18, s18, 0x2000
	s_addc_u32 s19, s19, 0
	s_cmp_lt_i32 s7, 64
	s_cbranch_scc1 .LBB0_979
